# P2 retention-tile head: both decay-table loads issued together, one wait (prologue de-serialisation)
# speedup vs baseline: 1.0024x; 1.0024x over previous
.LBB0_146:
	s_cmp_eq_u32 s67, 4
	s_mov_b64 s[4:5], -1
	s_cbranch_scc0 .LBB0_161
	v_mov_b32_e32 v0, s19
	ds_read_b64 v[0:1], v0
	s_waitcnt lgkmcnt(0)
	s_barrier
	v_readfirstlane_b32 s6, v0
	v_readfirstlane_b32 s36, v1
	s_and_saveexec_b64 s[4:5], s[0:1]
	s_cbranch_execz .LBB0_149
	v_mov_b32_e32 v0, s44
	ds_read2_b64 v[0:3], v0 offset1:1
	s_lshl_b32 s27, s26, 1
	v_and_or_b32 v4, s27, 2, v133
	v_lshlrev_b32_e32 v134, 2, v4
	s_waitcnt lgkmcnt(0)
	v_add_co_u32_e32 v0, vcc, v0, v134
	v_addc_co_u32_e32 v1, vcc, v1, v135, vcc
	v_add_co_u32_e32 v240, vcc, v2, v134
	v_addc_co_u32_e32 v241, vcc, v3, v135, vcc
	flat_load_dword v0, v[0:1]
	flat_load_dword v242, v[240:241]
	s_waitcnt vmcnt(0) lgkmcnt(0)
	v_mul_f32_e32 v4, v0, v164
	v_mul_f32_e32 v0, 0x3fb8aa3b, v4
	v_fma_f32 v1, v4, s45, -v0
	v_rndne_f32_e32 v5, v0
	v_fmac_f32_e32 v1, 0x32a5705f, v4
	v_sub_f32_e32 v0, v0, v5
	v_add_f32_e32 v0, v0, v1
	v_cvt_i32_f32_e32 v5, v5
	v_exp_f32_e32 v6, v0
	v_cmp_ngt_f32_e32 vcc, s46, v4
	v_ldexp_f32 v2, v6, v5
	s_nop 0
	v_cndmask_b32_e32 v2, 0, v2, vcc
	v_cmp_nlt_f32_e32 vcc, s47, v4
	s_nop 1
	v_cndmask_b32_e32 v2, v167, v2, vcc
	ds_write_b32 v165, v2
	v_mov_b32_e32 v0, v242
	s_waitcnt lgkmcnt(0)
	v_mul_f32_e32 v0, v0, v166
	v_mul_f32_e32 v1, 0x3fb8aa3b, v0
	v_fma_f32 v2, v0, s45, -v1
	v_rndne_f32_e32 v3, v1
	v_fmac_f32_e32 v2, 0x32a5705f, v0
	v_sub_f32_e32 v1, v1, v3
	v_add_f32_e32 v1, v1, v2
	v_cvt_i32_f32_e32 v3, v3
	v_exp_f32_e32 v1, v1
	v_cmp_ngt_f32_e32 vcc, s46, v0
	v_ldexp_f32 v1, v1, v3
	s_nop 0
	v_cndmask_b32_e32 v1, 0, v1, vcc
	v_cmp_nlt_f32_e32 vcc, s47, v0
	s_nop 1
	v_cndmask_b32_e32 v0, v167, v1, vcc
	ds_write_b32 v165, v0 offset:1024
